# P6: filler workgroups with blockIdx bit 3 set run adaLN chunk-2 item + W3B conversion before their GEMM units (streaming of the two halves no longer collides) on top of p7a
# baseline (speedup 1.0000x reference)
; #define PG8_WAIT_V(n) asm volatile("s_waitcnt vmcnt(" #n ")" ::: "memory")
;     const int tid = threadIdx.x, wid = __builtin_amdgcn_readfirstlane(tid >> 6), lane = tid & 63, wr = wid >> 2, wc = wid & 3, fr = lane & 15, fq = lane >> 4;
;     const int K = g.K, nt = K / BK;
;     unsigned voffA[2], voffB[2];
; #pragma unroll
;     for (int i = 0; i < 2; ++i) { int R, C; stage_rc(tid * 16 + i * 8192, R, C); const int Rb = Epi::PERM ? ((R & ~31) + perm32(R & 31)) : R;
;         voffA[i] = (unsigned)(R * K + C) * 2u; voffB[i] = (unsigned)(Rb * K + C) * 2u; }
;     const size_t kstep = (size_t)(BK * 2);
;     const size_t hstep = (size_t)HALF * K * 2;
;     const size_t tstep = 2 * hstep;
;     const unsigned ldsw = (unsigned)wid * 1024u;
;     const int aoff = lds_byte(wr * 64 + fr, fq * 8), boff = lds_byte(wc * 32 + fr, fq * 8);
;     ...
;     Unit cur, nxt; int ui = 0;
;     if (!S.next(0, cur)) return;
;     f32x4 acc[2][2][4][2];
; #pragma unroll
;     for (int a = 0; a < 2; ++a)
; #pragma unroll
;         for (int b = 0; b < 2; ++b)
; #pragma unroll
;             for (int m = 0; m < 4; ++m)
; #pragma unroll
;                 for (int n = 0; n < 2; ++n) acc[a][b][m][n] = (f32x4){0.f, 0.f, 0.f, 0.f};
;     bf16x8 At[4][2], B0[2][2], B1[2][2];
;     if constexpr (DIAG == 2 || DIAG == 3) { _Pragma("unroll") for (int i = 0; i < 4; ++i) _Pragma("unroll") for (int k = 0; k < 2; ++k) At[i][k] = (bf16x8){0,0,0,0,0,0,0,0}; _Pragma("unroll") for (int i = 0; i < 2; ++i) _Pragma("unroll") for (int k = 0; k < 2; ++k) { B0[i][k] = (bf16x8){0,0,0,0,0,0,0,0}; B1[i][k] = (bf16x8){0,0,0,0,0,0,0,0}; } }
;     const char* cA = (const char*)g.A + (size_t)cur.pm * tstep; const char* cB = (const char*)g.Bt + (size_t)cur.pn * tstep;
;     int kb = 0, ke = nt; if constexpr (Sched::SK) { kb = cur.kb; ke = cur.ke; }
;     const char* pA = cA + (size_t)kb * kstep; const char* pB = cB + (size_t)kb * kstep;
;     S.a_ready(cur);
;     if constexpr (SP2) {
;         PG8_STAGE(PG8_SB(0, 0), pB, voffB); PG8_STAGE(PG8_SB(0, 1), pB + hstep, voffB); PG8_STAGE(PG8_SA(0, 0), pA, voffA); PG8_STAGE(PG8_SA(0, 1), pA + hstep, voffA);
;         if (wr == 1) PG8_BAR;
;         PG8_WAIT_V(2); PG8_BAR;
;         PG8_STAGE(PG8_SB(1, 0), pB + kstep, voffB); PG8_STAGE(PG8_SA(1, 0), pA + kstep, voffA); PG8_STAGE(PG8_SB(1, 1), pB + hstep + kstep, voffB);
;         PG8_WAIT_V(6); PG8_BAR;
;     } else {
.Lp6_again:
	s_cmpk_eq_i32 s33, 0x100
	s_cbranch_scc0 .Lp6_norm
	s_cmp_eq_u32 s98, 12
	s_cbranch_scc1 .Lp6_norm
	s_cmp_lt_i32 s50, 32
	s_cbranch_scc1 .Lp6_norm
	s_bitcmp1_b32 s50, 3
	s_cbranch_scc0 .Lp6_norm
	v_writelane_b32 v253, s10, 32
	v_writelane_b32 v253, s11, 33
	v_writelane_b32 v253, s16, 34
	v_writelane_b32 v253, s17, 35
	v_writelane_b32 v253, s18, 36
	v_writelane_b32 v253, s19, 37
	v_writelane_b32 v253, s20, 38
	v_writelane_b32 v253, s21, 39
	v_writelane_b32 v253, s22, 40
	v_writelane_b32 v253, s23, 41
	v_writelane_b32 v253, s46, 42
	v_writelane_b32 v253, s48, 43
	v_writelane_b32 v253, s50, 44
	v_writelane_b32 v253, s51, 45
	v_writelane_b32 v253, s54, 46
	v_writelane_b32 v253, s58, 47
	v_writelane_b32 v253, s59, 48
	v_writelane_b32 v253, s88, 49
	v_writelane_b32 v253, s94, 50
	v_writelane_b32 v253, s95, 51
	v_writelane_b32 v253, s100, 52
	s_mov_b32 s98, 11
	v_lshrrev_b32_e32 v163, 1, v0
	v_and_b32_e32 v190, 15, v0
	s_branch .LBB0_528
.Lp6_norm:
	v_and_b32_e32 v2, 32, v0
	v_bitop3_b32 v165, v164, v2, 48 bitop3:0x6c
	v_lshrrev_b32_e32 v2, 5, v0
	v_lshrrev_b32_e32 v163, 1, v0
	v_and_b32_e32 v2, 4, v2
	v_bfe_u32 v3, v0, 2, 2
	v_and_b32_e32 v194, 24, v163
	v_bfe_u32 v192, v0, 2, 4
	v_or3_b32 v2, v2, v3, v194
	v_lshrrev_b32_e32 v3, 3, v0
	v_or_b32_e32 v193, 0x2000, v164
	v_and_or_b32 v201, v3, 48, v192
	v_and_or_b32 v198, v3, 32, v2
	v_lshrrev_b32_e32 v3, 7, v193
	s_movk_i32 s0, 0x70
	v_and_or_b32 v199, v3, s0, v192
	s_movk_i32 s0, 0x60
	v_and_or_b32 v200, v3, s0, v2
	s_ashr_i32 s0, s50, 31
	s_lshr_b32 s2, s0, 29
	s_add_i32 s2, s50, s2
	s_ashr_i32 s15, s2, 3
	s_and_b32 s2, s2, -8
	v_lshlrev_b32_e32 v2, 6, v0
	s_ashr_i32 s1, s33, 31
	s_sub_i32 s26, s50, s2
	v_and_b32_e32 v191, 64, v0
	v_lshlrev_b32_e32 v195, 1, v194
	v_and_b32_e32 v2, 0x3c0, v2
	v_and_b32_e32 v3, 32, v1
	s_cmp_lt_i32 s26, 0
	v_or_b32_e32 v197, v165, v191
	v_and_b32_e32 v190, 15, v0
	v_bitop3_b32 v196, v195, v3, v2 bitop3:0x36
	s_cselect_b64 s[6:7], -1, 0
	s_cmpk_gt_i32 s50, 0x11f
	v_readfirstlane_b32 s2, v0
	s_cbranch_scc1 .LBB0_512
	s_add_u32 s27, s30, 0x27d00000
	s_addc_u32 s34, s31, 0
	s_add_u32 s84, s30, 0x26d00000
	s_addc_u32 s85, s31, 0
	s_lshr_b32 s10, s2, 6
	s_lshr_b32 s3, s2, 8
	s_lshl_b32 s86, s10, 10
	s_and_b64 s[8:9], s[6:7], exec
	s_cselect_b32 s8, 37, 36
	s_mul_i32 s8, s26, s8
	s_add_i32 s8, s8, s15
	s_ashr_i32 s9, s8, 31
	s_lshr_b32 s9, s9, 26
	s_add_i32 s9, s8, s9
	s_ashr_i32 s11, s9, 6
	s_lshl_b32 s11, s11, 3
	s_sub_i32 s12, 36, s11
	s_min_i32 s12, s12, 8
	s_abs_i32 s13, s12
	v_cvt_f32_u32_e32 v2, s13
	s_sub_i32 s16, 0, s13
	s_andn2_b32 s9, s9, 63
	s_sub_i32 s8, s8, s9
	v_rcp_iflag_f32_e32 v2, v2
	s_abs_i32 s14, s8
	s_xor_b32 s9, s8, s12
	s_ashr_i32 s9, s9, 31
	v_mul_f32_e32 v2, 0x4f7ffffe, v2
	v_cvt_u32_f32_e32 v2, v2
	v_lshl_or_b32 v168, v198, 12, v197
	v_lshl_or_b32 v172, v200, 12, v197
	v_lshl_or_b32 v166, v201, 12, v197
	v_readfirstlane_b32 s17, v2
	s_mul_i32 s16, s16, s17
	s_mul_hi_u32 s16, s17, s16
	s_add_i32 s17, s17, s16
	s_mul_hi_u32 s16, s14, s17
	s_mul_i32 s17, s16, s13
	s_sub_i32 s14, s14, s17
	s_add_i32 s17, s16, 1
	s_sub_i32 s18, s14, s13
	s_cmp_ge_u32 s14, s13
	s_cselect_b32 s16, s17, s16
	s_cselect_b32 s14, s18, s14
	s_add_i32 s17, s16, 1
	s_cmp_ge_u32 s14, s13
	s_cselect_b32 s13, s17, s16
	s_xor_b32 s13, s13, s9
	s_sub_i32 s54, s13, s9
	s_mul_i32 s9, s54, s12
	s_sub_i32 s8, s8, s9
	s_add_i32 s72, s11, s8
	s_ashr_i32 s73, s72, 31
	s_ashr_i32 s55, s54, 31
	s_lshl_b64 s[8:9], s[72:73], 20
	s_lshl_b64 s[12:13], s[54:55], 20
	s_add_u32 s76, s84, s12
	s_addc_u32 s77, s85, s13
	s_add_i32 s55, s86, 0
	s_add_i32 m0, s55, 0x10000
	v_lshl_or_b32 v170, v199, 12, v197
	global_load_lds_dwordx4 v168, s[76:77]
	s_add_i32 m0, s55, 0x12000
	s_add_u32 s12, s76, 0x80000
	global_load_lds_dwordx4 v172, s[76:77]
	s_addc_u32 s13, s77, 0
	s_add_i32 m0, s55, 0x14000
	v_mov_b32_e32 v169, 0
	global_load_lds_dwordx4 v168, s[12:13]
	s_add_i32 m0, s55, 0x16000
	s_add_u32 s74, s27, s8
	s_addc_u32 s75, s34, s9
	s_add_i32 s73, s55, 0x2000
	global_load_lds_dwordx4 v172, s[12:13]
	s_mov_b32 m0, s55
	s_add_u32 s8, s74, 0x80000
	global_load_lds_dwordx4 v166, s[74:75]
	s_mov_b32 m0, s73
	s_addc_u32 s9, s75, 0
	s_add_i32 s87, s55, 0x4000
	global_load_lds_dwordx4 v170, s[74:75]
	s_mov_b32 m0, s87
	s_add_i32 s88, s55, 0x6000
	global_load_lds_dwordx4 v166, s[8:9]
	s_mov_b32 m0, s88
	v_mov_b32_e32 v173, v169
	global_load_lds_dwordx4 v170, s[8:9]
	v_mov_b32_e32 v167, v169
	v_mov_b32_e32 v171, v169
	s_cmp_eq_u32 s3, 1
	v_lshl_add_u64 v[8:9], s[76:77], 0, v[168:169]
	v_lshl_add_u64 v[6:7], s[76:77], 0, v[172:173]
	v_lshl_add_u64 v[2:3], s[74:75], 0, v[166:167]
	s_cselect_b64 s[8:9], -1, 0
	s_cmp_lg_u32 s3, 1
	v_lshl_add_u64 v[4:5], s[74:75], 0, v[170:171]
	s_cbranch_scc1 .LBB0_499
	s_barrier

; #define SEAM(k) do { if (IN(k) && IN((k) + 1)) xcd_barrier(bar); } while (0)
; __global__ void __launch_bounds__(NWAVES * 64, 2) mk_fwd(Args args) {
;     ...
;         if (rep == 0) { const int left8 = ((M / 256) * (NQ8 / 256)) % F.G;
;             if (cb >= left8) { const int ir = cb - left8, ni = F.G - left8;
;                 mod_chunk_partials(F, args, 2, ir, ni); __syncthreads(); { const int rank = ir * NWAVES + F.wave, nw = ni * NWAVES; conv_job<JOB_W3B>(F, args, rank, nw); } } } } } SEAM(6);
.LBB0_528:
	s_movk_i32 s99, 0x2b00
	s_mov_b32 s101, 1
	s_cmp_eq_u32 s98, 12
	s_cbranch_scc0 .Lp6_fill
	s_mov_b32 s98, 2
	s_branch .Lq_done

; #define SEAM(k) do { if (IN(k) && IN((k) + 1)) xcd_barrier(bar); } while (0)
; __global__ void __launch_bounds__(NWAVES * 64, 2) mk_fwd(Args args) {
;     ...
;         if (rep == 0) { const int left8 = ((M / 256) * (NQ8 / 256)) % F.G;
;             if (cb >= left8) { const int ir = cb - left8, ni = F.G - left8;
;                 mod_chunk_partials(F, args, 2, ir, ni); __syncthreads(); { const int rank = ir * NWAVES + F.wave, nw = ni * NWAVES; conv_job<JOB_W3B>(F, args, rank, nw); } } } } } SEAM(6);
.Lq_done:
	s_cmp_eq_u32 s98, 11
	s_cbranch_scc0 .Lp6_exit
	s_mov_b32 s98, 12
	v_readlane_b32 s10, v253, 32
	v_readlane_b32 s11, v253, 33
	v_readlane_b32 s16, v253, 34
	v_readlane_b32 s17, v253, 35
	v_readlane_b32 s18, v253, 36
	v_readlane_b32 s19, v253, 37
	v_readlane_b32 s20, v253, 38
	v_readlane_b32 s21, v253, 39
	v_readlane_b32 s22, v253, 40
	v_readlane_b32 s23, v253, 41
	v_readlane_b32 s46, v253, 42
	v_readlane_b32 s48, v253, 43
	v_readlane_b32 s50, v253, 44
	v_readlane_b32 s51, v253, 45
	v_readlane_b32 s54, v253, 46
	v_readlane_b32 s58, v253, 47
	v_readlane_b32 s59, v253, 48
	v_readlane_b32 s88, v253, 49
	v_readlane_b32 s94, v253, 50
	v_readlane_b32 s95, v253, 51
	v_readlane_b32 s100, v253, 52
	s_waitcnt vmcnt(0) lgkmcnt(0)
	s_barrier
	s_branch .Lp6_again
